# DA loop: first-half row-max tail in two ops instead of four
# speedup vs baseline: 1.0027x; 1.0020x over previous
; #define SCHED_FENCE() __builtin_amdgcn_sched_barrier(0)
; __device__ __forceinline__ void da_phase(LAS unsigned char* lds, const bf16* Q, const bf16* Kb, const bf16* Vb, bf16* O, const float* lq1, const float* lk1, const float* lq2, const float* lk2,
;                                          const float* t5, int G, int wave, int lane, int tid) {
;     ...
;             p1 = __builtin_amdgcn_mfma_f32_32x32x16_bf16(__builtin_bit_cast(H8, kf[0]), qf[0], p1, 0, 0, 0); a0 = __builtin_fmaxf(__builtin_fmaxf(p0[0], p0[1]), p0[2]); a0 = __builtin_fmaxf(__builtin_fmaxf(a0, p0[3]), p0[4]); asm volatile("" : "+v"(a0)); SCHED_FENCE();
;             p1 = __builtin_amdgcn_mfma_f32_32x32x16_bf16(__builtin_bit_cast(H8, kf[1]), qf[1], p1, 0, 0, 0); a0 = __builtin_fmaxf(__builtin_fmaxf(a0, p0[5]), p0[6]); a0 = __builtin_fmaxf(__builtin_fmaxf(a0, p0[7]), p0[8]); asm volatile("" : "+v"(a0)); SCHED_FENCE();
;             p1 = __builtin_amdgcn_mfma_f32_32x32x16_bf16(__builtin_bit_cast(H8, kf[2]), qf[2], p1, 0, 0, 0); a0 = __builtin_fmaxf(__builtin_fmaxf(a0, p0[9]), p0[10]); a0 = __builtin_fmaxf(__builtin_fmaxf(a0, p0[11]), p0[12]); asm volatile("" : "+v"(a0)); SCHED_FENCE();
;             p1 = __builtin_amdgcn_mfma_f32_32x32x16_bf16(__builtin_bit_cast(H8, kf[3]), qf[3], p1, 0, 0, 0); a0 = __builtin_fmaxf(__builtin_fmaxf(a0, p0[13]), p0[14]); a0 = __builtin_fmaxf(a0, p0[15]); asm volatile("" : "+v"(a0)); SCHED_FENCE();
;             if (t + 2 < NT) DA_DMA_V(t + 2, (t + 2) & 3);
.LBB0_217:
	s_waitcnt lgkmcnt(0)
	v_mfma_f32_32x32x16_bf16 v[80:95], v[176:179], v[120:123], v[236:251]
	ds_read_b64_tr_b16 v[160:161], v234 offset:0
	ds_read_b64_tr_b16 v[162:163], v234 offset:512
	ds_read_b64_tr_b16 v[156:157], v234 offset:1024
	ds_read_b64_tr_b16 v[158:159], v234 offset:1536
	v_max3_f32 v0, v96, v97, v98
	v_max3_f32 v0, v0, v99, v100
	v_mfma_f32_32x32x16_bf16 v[80:95], v[172:175], v[124:127], v[80:95]
	ds_read_b64_tr_b16 v[152:153], v234 offset:2048
	ds_read_b64_tr_b16 v[154:155], v234 offset:2560
	ds_read_b64_tr_b16 v[148:149], v234 offset:3072
	ds_read_b64_tr_b16 v[150:151], v234 offset:3584
	v_max3_f32 v0, v0, v101, v102
	v_max3_f32 v0, v0, v103, v104
	v_mfma_f32_32x32x16_bf16 v[80:95], v[168:171], v[128:131], v[80:95]
	ds_read_b64_tr_b16 v[144:145], v234 offset:4096
	ds_read_b64_tr_b16 v[146:147], v234 offset:4608
	ds_read_b64_tr_b16 v[10:11], v234 offset:5120
	ds_read_b64_tr_b16 v[12:13], v234 offset:5632
	v_max3_f32 v0, v0, v105, v106
	v_max3_f32 v0, v0, v107, v108
	v_mfma_f32_32x32x16_bf16 v[80:95], v[164:167], v[132:135], v[80:95]
	ds_read_b64_tr_b16 v[6:7], v234 offset:6144
	ds_read_b64_tr_b16 v[8:9], v234 offset:6656
	ds_read_b64_tr_b16 v[2:3], v234 offset:7168
	ds_read_b64_tr_b16 v[4:5], v234 offset:7680
	v_max3_f32 v0, v0, v109, v110
	v_max_f32_e32 v0, v0, v111
	s_cmp_gt_u32 s45, s39
	s_cbranch_scc1 .Lda_vskip
	s_add_i32 s0, s16, 0x4000
	s_and_b32 s0, s0, 0xc000
	s_add_i32 s20, s3, s0
	s_add_i32 m0, s20, 0xc000
	s_nop 0
	global_load_lds_dwordx4 v196, s[74:75]
	s_add_i32 m0, m0, 0x400
	s_nop 0
	global_load_lds_dwordx4 v205, s[74:75]
	s_add_u32 s74, s74, 0x4000
	s_addc_u32 s75, s75, 0
